# prompt attention loop: V fragments of all four PV groups read up front with counted lgkmcnt, next-tile V DMA left in flight across the back-edge (vmcnt 4 before K copies), row max via v_max3, packed s
# speedup vs baseline: 1.0104x; 1.0024x over previous
.LBB0_529:
	v_max3_f32 v1, v143, v142, v144
	s_nop 3
	v_max3_f32 v146, v145, v141, v140
	v_max3_f32 v1, v1, v138, v139
	v_max_f32_e32 v1, v1, v146
	s_waitcnt lgkmcnt(0)
	v_fmamk_f32 v146, v1, 0x3e38aa3b, v210
	v_cndmask_b32_e64 v148, v1, v146, s[2:3]
	v_add_f32_e32 v1, 0x41000000, v209
	v_cmp_gt_f32_e32 vcc, v148, v1
	v_max3_f32 v1, v135, v134, v136
	v_max3_f32 v146, v137, v133, v132
	v_max3_f32 v1, v1, v130, v131
	v_max_f32_e32 v1, v1, v146
	v_fmamk_f32 v146, v1, 0x3e38aa3b, v210
	v_cndmask_b32_e64 v147, v1, v146, s[2:3]
	v_add_f32_e32 v1, 0x41000000, v208
	v_cmp_gt_f32_e64 s[4:5], v147, v1
	v_max3_f32 v1, v127, v126, v128
	v_max3_f32 v146, v129, v125, v124
	v_max3_f32 v1, v1, v122, v123
	v_max_f32_e32 v1, v1, v146
	v_fmamk_f32 v146, v1, 0x3e38aa3b, v210
	v_cndmask_b32_e64 v146, v1, v146, s[2:3]
	v_add_f32_e32 v1, 0x41000000, v207
	s_or_b64 s[4:5], vcc, s[4:5]
	v_cmp_gt_f32_e32 vcc, v146, v1
	v_max3_f32 v1, v119, v118, v120
	v_max3_f32 v149, v121, v117, v116
	v_max3_f32 v1, v1, v114, v115
	v_max_f32_e32 v1, v1, v149
	v_fmamk_f32 v149, v1, 0x3e38aa3b, v210
	v_cndmask_b32_e64 v1, v1, v149, s[2:3]
	v_add_f32_e32 v149, 0x41000000, v206
	s_or_b64 s[4:5], s[4:5], vcc
	v_cmp_gt_f32_e32 vcc, v1, v149
	s_or_b64 vcc, s[4:5], vcc
	s_cbranch_vccz .LBB0_531
	v_mov_b32_e32 v149, v148
	s_nop 1
	v_permlane16_swap_b32_e32 v148, v149
	v_max_f32_e32 v149, v149, v149
	v_max_f32_e32 v148, v148, v148
	v_max_f32_e32 v148, v148, v149
	v_mov_b32_e32 v149, v148
	s_nop 1
	v_permlane32_swap_b32_e32 v148, v149
	v_max3_f32 v160, v209, v148, v149
	v_sub_f32_e32 v148, v209, v160
	v_exp_f32_e32 v148, v148
	v_mov_b32_e32 v209, v160
	v_pk_mul_f32 v[92:93], v[92:93], v[148:149] op_sel_hi:[1,0]
	v_pk_mul_f32 v[90:91], v[90:91], v[148:149] op_sel_hi:[1,0]
	v_pk_mul_f32 v[96:97], v[96:97], v[148:149] op_sel_hi:[1,0]
	v_pk_mul_f32 v[94:95], v[94:95], v[148:149] op_sel_hi:[1,0]
	v_pk_mul_f32 v[88:89], v[88:89], v[148:149] op_sel_hi:[1,0]
	v_pk_mul_f32 v[86:87], v[86:87], v[148:149] op_sel_hi:[1,0]
	v_mov_b32_e32 v149, v147
	s_nop 1
	v_permlane16_swap_b32_e32 v147, v149
	v_max_f32_e32 v149, v149, v149
	v_max_f32_e32 v147, v147, v147
	v_max_f32_e32 v147, v147, v149
	v_mov_b32_e32 v149, v147
	s_nop 1
	v_permlane32_swap_b32_e32 v147, v149
	v_max3_f32 v147, v208, v147, v149
	v_sub_f32_e32 v149, v208, v147
	v_pk_mul_f32 v[84:85], v[84:85], v[148:149] op_sel_hi:[1,0]
	v_pk_mul_f32 v[82:83], v[82:83], v[148:149] op_sel_hi:[1,0]
	v_mov_b32_e32 v159, v148
	v_mov_b32_e32 v148, v146
	s_nop 1
	v_permlane16_swap_b32_e32 v146, v148
	v_exp_f32_e32 v158, v149
	v_max_f32_e32 v148, v148, v148
	v_max_f32_e32 v146, v146, v146
	v_max_f32_e32 v146, v146, v148
	v_mov_b32_e32 v148, v146
	s_nop 1
	v_permlane32_swap_b32_e32 v146, v148
	v_pk_mul_f32 v[152:153], v[152:153], v[158:159]
	v_pk_mul_f32 v[48:49], v[48:49], v[158:159] op_sel_hi:[1,0]
	v_pk_mul_f32 v[46:47], v[46:47], v[158:159] op_sel_hi:[1,0]
	v_pk_mul_f32 v[44:45], v[44:45], v[158:159] op_sel_hi:[1,0]
	v_pk_mul_f32 v[42:43], v[42:43], v[158:159] op_sel_hi:[1,0]
	v_pk_mul_f32 v[40:41], v[40:41], v[158:159] op_sel_hi:[1,0]
	v_max3_f32 v159, v207, v146, v148
	v_mov_b32_e32 v148, v1
	s_nop 1
	v_permlane16_swap_b32_e32 v1, v148
	v_max_f32_e32 v148, v148, v148
	v_max_f32_e32 v1, v1, v1
	v_max_f32_e32 v1, v1, v148
	v_mov_b32_e32 v148, v1
	s_nop 1
	v_permlane32_swap_b32_e32 v1, v148
	v_sub_f32_e32 v146, v207, v159
	v_max3_f32 v1, v206, v1, v148
	v_exp_f32_e32 v146, v146
	v_sub_f32_e32 v148, v206, v1
	v_exp_f32_e32 v148, v148
	v_pk_mul_f32 v[38:39], v[38:39], v[158:159] op_sel_hi:[1,0]
	v_mov_b32_e32 v149, v146
	v_pk_mul_f32 v[36:37], v[36:37], v[158:159] op_sel_hi:[1,0]
	v_pk_mul_f32 v[34:35], v[34:35], v[158:159] op_sel_hi:[1,0]
	v_pk_mul_f32 v[32:33], v[32:33], v[146:147] op_sel_hi:[1,0]
	v_pk_mul_f32 v[30:31], v[30:31], v[146:147] op_sel_hi:[1,0]
	v_pk_mul_f32 v[28:29], v[28:29], v[146:147] op_sel_hi:[1,0]
	v_pk_mul_f32 v[26:27], v[26:27], v[146:147] op_sel_hi:[1,0]
	v_pk_mul_f32 v[24:25], v[24:25], v[146:147] op_sel_hi:[1,0]
	v_pk_mul_f32 v[22:23], v[22:23], v[146:147] op_sel_hi:[1,0]
	v_pk_mul_f32 v[20:21], v[20:21], v[146:147] op_sel_hi:[1,0]
	v_pk_mul_f32 v[18:19], v[18:19], v[146:147] op_sel_hi:[1,0]
	v_pk_mul_f32 v[150:151], v[150:151], v[148:149]
	v_pk_mul_f32 v[16:17], v[16:17], v[148:149] op_sel_hi:[1,0]
	v_pk_mul_f32 v[14:15], v[14:15], v[148:149] op_sel_hi:[1,0]
	v_pk_mul_f32 v[12:13], v[12:13], v[148:149] op_sel_hi:[1,0]
	v_pk_mul_f32 v[10:11], v[10:11], v[148:149] op_sel_hi:[1,0]
	v_pk_mul_f32 v[8:9], v[8:9], v[148:149] op_sel_hi:[1,0]
	v_pk_mul_f32 v[6:7], v[6:7], v[148:149] op_sel_hi:[1,0]
	v_pk_mul_f32 v[4:5], v[4:5], v[148:149] op_sel_hi:[1,0]
	v_pk_mul_f32 v[2:3], v[2:3], v[148:149] op_sel_hi:[1,0]
	v_mov_b32_e32 v206, v1
	v_mov_b32_e32 v207, v159
	v_mov_b32_e32 v208, v147
.LBB0_531:
	s_andn2_b64 vcc, exec, s[14:15]
	s_mov_b64 s[2:3], -1
	s_cbranch_vccnz .LBB0_533
	v_pk_add_f32 v[142:143], v[142:143], v[208:209] op_sel:[0,1] op_sel_hi:[1,1] neg_lo:[0,1] neg_hi:[0,1]
	v_pk_add_f32 v[144:145], v[144:145], v[208:209] op_sel:[0,1] op_sel_hi:[1,1] neg_lo:[0,1] neg_hi:[0,1]
	v_pk_add_f32 v[138:139], v[138:139], v[208:209] op_sel:[0,1] op_sel_hi:[1,1] neg_lo:[0,1] neg_hi:[0,1]
	v_pk_add_f32 v[140:141], v[140:141], v[208:209] op_sel:[0,1] op_sel_hi:[1,1] neg_lo:[0,1] neg_hi:[0,1]
	v_exp_f32_e32 v147, v142
	v_exp_f32_e32 v149, v143
	v_pk_add_f32 v[134:135], v[134:135], v[208:209] op_sel_hi:[1,0] neg_lo:[0,1] neg_hi:[0,1]
	v_exp_f32_e32 v159, v144
	v_exp_f32_e32 v161, v145
	v_pk_add_f32 v[136:137], v[136:137], v[208:209] op_sel_hi:[1,0] neg_lo:[0,1] neg_hi:[0,1]
	v_exp_f32_e32 v163, v138
	v_exp_f32_e32 v165, v139
	v_pk_add_f32 v[130:131], v[130:131], v[208:209] op_sel_hi:[1,0] neg_lo:[0,1] neg_hi:[0,1]
	v_exp_f32_e32 v167, v140
	v_exp_f32_e32 v169, v141
	v_pk_add_f32 v[132:133], v[132:133], v[208:209] op_sel_hi:[1,0] neg_lo:[0,1] neg_hi:[0,1]
	v_exp_f32_e32 v146, v134
	v_exp_f32_e32 v148, v135
	v_pk_add_f32 v[126:127], v[126:127], v[206:207] op_sel:[0,1] op_sel_hi:[1,1] neg_lo:[0,1] neg_hi:[0,1]
	v_exp_f32_e32 v158, v136
	v_exp_f32_e32 v160, v137
	v_pk_add_f32 v[128:129], v[128:129], v[206:207] op_sel:[0,1] op_sel_hi:[1,1] neg_lo:[0,1] neg_hi:[0,1]
	v_exp_f32_e32 v162, v130
	v_exp_f32_e32 v164, v131
	v_pk_add_f32 v[122:123], v[122:123], v[206:207] op_sel:[0,1] op_sel_hi:[1,1] neg_lo:[0,1] neg_hi:[0,1]
	v_exp_f32_e32 v166, v132
	v_exp_f32_e32 v168, v133
	v_pk_add_f32 v[124:125], v[124:125], v[206:207] op_sel:[0,1] op_sel_hi:[1,1] neg_lo:[0,1] neg_hi:[0,1]
	v_exp_f32_e32 v211, v126
	v_exp_f32_e32 v173, v127
	v_pk_add_f32 v[118:119], v[118:119], v[206:207] op_sel_hi:[1,0] neg_lo:[0,1] neg_hi:[0,1]
	v_exp_f32_e32 v175, v128
	v_exp_f32_e32 v177, v129
	v_pk_add_f32 v[120:121], v[120:121], v[206:207] op_sel_hi:[1,0] neg_lo:[0,1] neg_hi:[0,1]
	v_exp_f32_e32 v179, v122
	v_exp_f32_e32 v181, v123
	v_pk_add_f32 v[114:115], v[114:115], v[206:207] op_sel_hi:[1,0] neg_lo:[0,1] neg_hi:[0,1]
	v_exp_f32_e32 v183, v124
	v_exp_f32_e32 v185, v125
	v_sub_f32_e32 v1, v116, v206
	v_sub_f32_e32 v212, v117, v206
	v_exp_f32_e32 v172, v118
	v_exp_f32_e32 v174, v119
	v_exp_f32_e32 v176, v120
	v_exp_f32_e32 v178, v121
	v_exp_f32_e32 v180, v114
	v_exp_f32_e32 v182, v115
	v_exp_f32_e32 v184, v1
	v_pk_add_f32 v[170:171], v[146:147], 0 op_sel_hi:[1,0]
	v_add_f32_e32 v1, 0, v211
	v_pk_add_f32 v[170:171], v[148:149], v[170:171]
	v_pk_add_f32 v[186:187], v[172:173], v[0:1]
	v_pk_add_f32 v[170:171], v[158:159], v[170:171]
	v_pk_add_f32 v[186:187], v[174:175], v[186:187]
	v_pk_add_f32 v[170:171], v[160:161], v[170:171]
	v_pk_add_f32 v[186:187], v[176:177], v[186:187]
	v_pk_add_f32 v[170:171], v[162:163], v[170:171]
	v_pk_add_f32 v[186:187], v[178:179], v[186:187]
	v_pk_add_f32 v[170:171], v[164:165], v[170:171]
	v_pk_add_f32 v[186:187], v[180:181], v[186:187]
	v_pk_add_f32 v[170:171], v[166:167], v[170:171]
	v_pk_add_f32 v[186:187], v[182:183], v[186:187]
	v_pk_add_f32 v[170:171], v[168:169], v[170:171]
	v_pk_add_f32 v[186:187], v[184:185], v[186:187]
	s_mov_b64 s[2:3], 0

.LBB0_539:
	s_lshl_b32 s2, s21, 12
	s_add_i32 s2, s7, s2
	v_add_f32_e32 v186, v1, v186
	v_add3_u32 v1, s2, v201, v200
	v_add3_u32 v234, s2, v202, v200
	v_add3_u32 v235, s2, v203, v200
	v_add3_u32 v236, s2, v204, v200
	ds_read_b64_tr_b16 v[130:131], v1
	ds_read_b64_tr_b16 v[132:133], v1 offset:2048
	ds_read_b64_tr_b16 v[214:215], v234
	ds_read_b64_tr_b16 v[216:217], v234 offset:2048
	ds_read_b64_tr_b16 v[218:219], v235
	ds_read_b64_tr_b16 v[220:221], v235 offset:2048
	ds_read_b64_tr_b16 v[222:223], v236
	ds_read_b64_tr_b16 v[224:225], v236 offset:2048
	s_add_i32 s19, s19, 32
	v_pk_add_f32 v[152:153], v[152:153], v[170:171]
	s_waitcnt lgkmcnt(6)
	v_mfma_f32_16x16x32_bf16 v[90:93], v[130:133], v[122:125], v[90:93]
	v_add_f32_e64 v150, v150, v186
	v_add_f32_e64 v151, v151, v187
	v_add_u32_e32 v205, 0xffffff80, v205
	s_cmp_gt_u32 s20, 16
	v_mfma_f32_16x16x32_bf16 v[46:49], v[130:133], v[126:129], v[46:49]
	v_mfma_f32_16x16x32_bf16 v[30:33], v[130:133], v[114:117], v[30:33]
	v_mfma_f32_16x16x32_bf16 v[14:17], v[130:133], v[118:121], v[14:17]
	s_waitcnt lgkmcnt(4)
	v_mfma_f32_16x16x32_bf16 v[94:97], v[214:217], v[122:125], v[94:97]
	v_mfma_f32_16x16x32_bf16 v[42:45], v[214:217], v[126:129], v[42:45]
	v_mfma_f32_16x16x32_bf16 v[26:29], v[214:217], v[114:117], v[26:29]
	v_mfma_f32_16x16x32_bf16 v[10:13], v[214:217], v[118:121], v[10:13]
	s_waitcnt lgkmcnt(2)
	v_mfma_f32_16x16x32_bf16 v[86:89], v[218:221], v[122:125], v[86:89]
	v_mfma_f32_16x16x32_bf16 v[38:41], v[218:221], v[126:129], v[38:41]
	v_mfma_f32_16x16x32_bf16 v[22:25], v[218:221], v[114:117], v[22:25]
	v_mfma_f32_16x16x32_bf16 v[6:9], v[218:221], v[118:121], v[6:9]
	s_waitcnt lgkmcnt(0)
	v_mfma_f32_16x16x32_bf16 v[82:85], v[222:225], v[122:125], v[82:85]
	v_mfma_f32_16x16x32_bf16 v[34:37], v[222:225], v[126:129], v[34:37]
	v_mfma_f32_16x16x32_bf16 v[18:21], v[222:225], v[114:117], v[18:21]
	v_mfma_f32_16x16x32_bf16 v[2:5], v[222:225], v[118:121], v[2:5]
	s_cbranch_scc1 .LBB0_541
	s_waitcnt vmcnt(4)
	v_mov_b64_e32 v[116:117], v[108:109]
	v_mov_b64_e32 v[148:149], v[112:113]
	v_mov_b64_e32 v[120:121], v[100:101]
	v_mov_b64_e32 v[124:125], v[104:105]
	v_mov_b64_e32 v[114:115], v[106:107]
	v_mov_b64_e32 v[146:147], v[110:111]
	v_mov_b64_e32 v[118:119], v[98:99]
	v_mov_b64_e32 v[122:123], v[102:103]
	s_branch .LBB0_525
